# ssd_unit2 x loads: one running row pointer with offset immediates instead of 16 separately computed 64-bit addresses (fewer vector instructions in an issue-bound loop)
# baseline (speedup 1.0000x reference)
.LBB0_280:
	s_or_b64 exec, exec, s[0:1]
	v_ashrrev_i32_e32 v35, 31, v34
	v_lshlrev_b64 v[58:59], 11, v[34:35]
	v_lshl_add_u64 v[58:59], v[78:79], 0, v[58:59]
	v_mov_b32_e32 v60, 0x1000
	v_mov_b32_e32 v61, 0
	global_load_ushort v127, v[58:59], off
	global_load_ushort v132, v[58:59], off offset:2048
	v_lshl_add_u64 v[58:59], v[58:59], 0, v[60:61]
	global_load_ushort v156, v[58:59], off
	global_load_ushort v147, v[58:59], off offset:2048
	v_lshl_add_u64 v[58:59], v[58:59], 0, v[60:61]
	global_load_ushort v134, v[58:59], off
	global_load_ushort v133, v[58:59], off offset:2048
	v_lshl_add_u64 v[58:59], v[58:59], 0, v[60:61]
	global_load_ushort v131, v[58:59], off
	global_load_ushort v130, v[58:59], off offset:2048
	v_lshl_add_u64 v[58:59], v[58:59], 0, v[60:61]
	global_load_ushort v129, v[58:59], off
	global_load_ushort v93, v[58:59], off offset:2048
	v_lshl_add_u64 v[58:59], v[58:59], 0, v[60:61]
	global_load_ushort v128, v[58:59], off
	global_load_ushort v88, v[58:59], off offset:2048
	v_lshl_add_u64 v[58:59], v[58:59], 0, v[60:61]
	global_load_ushort v89, v[58:59], off
	global_load_ushort v90, v[58:59], off offset:2048
	v_lshl_add_u64 v[58:59], v[58:59], 0, v[60:61]
	global_load_ushort v91, v[58:59], off
	global_load_ushort v92, v[58:59], off offset:2048
	ds_read_b128 v[38:41], v106
	ds_read_b128 v[34:37], v106 offset:16
	s_waitcnt lgkmcnt(0)
	v_sub_f32_e32 v34, v0, v34
	v_mul_f32_e32 v34, 0x3fb8aa3b, v34
	v_exp_f32_e32 v140, v34
	v_sub_f32_e32 v34, v0, v35
	v_mul_f32_e32 v34, 0x3fb8aa3b, v34
	ds_read_b128 v[50:53], v106 offset:32
	ds_read_b128 v[58:61], v106 offset:48
	v_exp_f32_e32 v141, v34
	v_sub_f32_e32 v34, v0, v36
	v_mul_f32_e32 v34, 0x3fb8aa3b, v34
	v_exp_f32_e32 v86, v34
	v_sub_f32_e32 v34, v0, v37
	v_mul_f32_e32 v34, 0x3fb8aa3b, v34
	v_exp_f32_e32 v87, v34
	s_waitcnt lgkmcnt(1)
	v_sub_f32_e32 v34, v0, v50
	v_mul_f32_e32 v34, 0x3fb8aa3b, v34
	v_exp_f32_e32 v56, v34
	v_sub_f32_e32 v34, v0, v51
	v_mul_f32_e32 v34, 0x3fb8aa3b, v34
	v_exp_f32_e32 v57, v34
	v_sub_f32_e32 v34, v0, v52
	s_waitcnt vmcnt(16)
	v_lshlrev_b32_e32 v42, 16, v42
	v_lshlrev_b32_e32 v43, 16, v43
	v_lshlrev_b32_e32 v47, 16, v47
	v_mov_b32_e32 v46, v43
	v_mul_f32_e32 v34, 0x3fb8aa3b, v34
	v_pk_fma_f32 v[42:43], v[68:69], v[42:43], v[76:77]
	v_exp_f32_e32 v54, v34
	v_sub_f32_e32 v34, v0, v53
	v_pk_fma_f32 v[42:43], v[70:71], v[46:47], v[42:43]
	v_mov_b32_e32 v48, v47
	v_mul_f32_e32 v34, 0x3fb8aa3b, v34
	v_sub_f32_e32 v38, v0, v38
	v_exp_f32_e32 v55, v34
	s_waitcnt lgkmcnt(0)
	v_sub_f32_e32 v34, v0, v58
	v_mul_f32_e32 v38, 0x3fb8aa3b, v38
	v_mul_f32_e32 v34, 0x3fb8aa3b, v34
	v_exp_f32_e32 v136, v38
	v_sub_f32_e32 v38, v0, v39
	v_exp_f32_e32 v50, v34
	v_sub_f32_e32 v34, v0, v59
	v_mul_f32_e32 v38, 0x3fb8aa3b, v38
	v_mul_f32_e32 v34, 0x3fb8aa3b, v34
	v_exp_f32_e32 v137, v38
	v_sub_f32_e32 v38, v0, v40
	v_exp_f32_e32 v51, v34
	v_sub_f32_e32 v34, v0, v60
	v_mul_f32_e32 v38, 0x3fb8aa3b, v38
	v_mul_f32_e32 v34, 0x3fb8aa3b, v34
	v_exp_f32_e32 v138, v38
	v_sub_f32_e32 v38, v0, v41
	v_exp_f32_e32 v52, v34
	v_sub_f32_e32 v34, v0, v61
	v_mul_f32_e32 v38, 0x3fb8aa3b, v38
	v_mul_f32_e32 v34, 0x3fb8aa3b, v34
	v_exp_f32_e32 v139, v38
	v_exp_f32_e32 v53, v34
	ds_read_b128 v[34:37], v106 offset:304
	ds_read_b128 v[38:41], v106 offset:288
	s_waitcnt vmcnt(15)
	v_lshlrev_b32_e32 v49, 16, v127
	v_pk_fma_f32 v[42:43], v[72:73], v[48:49], v[42:43]
	v_mov_b32_e32 v46, v49
	v_pk_fma_f32 v[48:49], v[68:69], v[48:49], v[76:77]
	s_waitcnt vmcnt(2)
	v_lshlrev_b32_e32 v63, 16, v90
	s_waitcnt vmcnt(1)
	v_lshlrev_b32_e32 v65, 16, v91
	s_waitcnt vmcnt(0)
	v_lshlrev_b32_e32 v61, 16, v92
	v_lshlrev_b32_e32 v90, 16, v93
	v_lshlrev_b32_e32 v91, 16, v128
	v_lshlrev_b32_e32 v143, 16, v129
	v_lshlrev_b32_e32 v142, 16, v130
	v_lshlrev_b32_e32 v145, 16, v131
	v_lshlrev_b32_e32 v146, 16, v132
	v_mov_b32_e32 v47, v146
	v_pk_fma_f32 v[42:43], v[74:75], v[46:47], v[42:43]
	v_pk_fma_f32 v[46:47], v[70:71], v[46:47], v[48:49]
	v_mul_f32_e32 v127, 0xbfb8aa3b, v42
	v_exp_f32_e32 v127, v127
	v_mul_f32_e32 v128, 0xbfb8aa3b, v43
	v_exp_f32_e32 v150, v128
	v_pk_fma_f32 v[92:93], v[68:69], v[142:143], v[76:77]
	v_add_f32_e32 v127, 1.0, v127
	v_rcp_f32_e32 v152, v127
	v_add_f32_e32 v127, 1.0, v150
	v_lshlrev_b32_e32 v144, 16, v133
	v_lshlrev_b32_e32 v151, 16, v134
	ds_read_b128 v[128:131], v106 offset:272
	ds_read_b128 v[132:135], v106 offset:256
	v_rcp_f32_e32 v153, v127
	v_lshlrev_b32_e32 v150, 16, v147
	v_lshlrev_b32_e32 v147, 16, v156
	v_pk_fma_f32 v[46:47], v[72:73], v[146:147], v[46:47]
	v_pk_mul_f32 v[42:43], v[42:43], v[152:153]
	v_pk_fma_f32 v[154:155], v[68:69], v[150:151], v[76:77]
	s_waitcnt lgkmcnt(0)
	v_pk_mul_f32 v[42:43], v[42:43], v[132:133]
	v_pk_mov_b32 v[132:133], v[146:147], v[150:151] op_sel:[1,0]
	v_pk_mul_f32 v[136:137], v[42:43], v[136:137]
	v_pk_fma_f32 v[48:49], v[74:75], v[132:133], v[46:47]
	v_pk_fma_f32 v[148:149], v[68:69], v[144:145], v[76:77]
	v_mul_f32_e32 v46, 0xbfb8aa3b, v48
	v_exp_f32_e32 v46, v46
	v_mul_f32_e32 v47, 0xbfb8aa3b, v49
	v_exp_f32_e32 v47, v47
	v_lshlrev_b64 v[44:45], 11, v[44:45]
	v_add_f32_e32 v46, 1.0, v46
	v_rcp_f32_e32 v152, v46
	v_add_f32_e32 v46, 1.0, v47
	v_rcp_f32_e32 v153, v46
	v_cvt_pk_bf16_f32 v46, v42, v43
	v_cvt_pk_bf16_f32 v42, v136, v137
	v_pk_fma_f32 v[136:137], v[68:69], v[146:147], v[76:77]
	v_pk_mov_b32 v[146:147], v[150:151], v[144:145] op_sel:[1,0]
	v_pk_fma_f32 v[132:133], v[70:71], v[132:133], v[136:137]
	v_pk_mul_f32 v[48:49], v[48:49], v[152:153]
	v_pk_fma_f32 v[132:133], v[72:73], v[150:151], v[132:133]
	v_pk_mul_f32 v[48:49], v[48:49], v[134:135]
	v_pk_fma_f32 v[132:133], v[74:75], v[146:147], v[132:133]
	v_pk_mul_f32 v[136:137], v[48:49], v[138:139]
	v_mul_f32_e32 v43, 0xbfb8aa3b, v132
	v_exp_f32_e32 v43, v43
	v_mul_f32_e32 v47, 0xbfb8aa3b, v133
	v_exp_f32_e32 v47, v47
	v_lshlrev_b32_e32 v58, 16, v88
	v_add_f32_e32 v43, 1.0, v43
	v_rcp_f32_e32 v134, v43
	v_add_f32_e32 v43, 1.0, v47
	v_rcp_f32_e32 v135, v43
	v_cvt_pk_bf16_f32 v47, v48, v49
	v_cvt_pk_bf16_f32 v43, v136, v137
	v_lshlrev_b32_e32 v59, 16, v89
	v_pk_mul_f32 v[48:49], v[132:133], v[134:135]
	v_pk_fma_f32 v[134:135], v[70:71], v[146:147], v[154:155]
	v_pk_mov_b32 v[132:133], v[144:145], v[142:143] op_sel:[1,0]
	v_pk_fma_f32 v[134:135], v[72:73], v[144:145], v[134:135]
	v_pk_mul_f32 v[48:49], v[48:49], v[128:129]
	v_pk_fma_f32 v[136:137], v[74:75], v[132:133], v[134:135]
	v_pk_fma_f32 v[132:133], v[70:71], v[132:133], v[148:149]
	v_mul_f32_e32 v127, 0xbfb8aa3b, v136
	v_exp_f32_e32 v127, v127
	v_mul_f32_e32 v134, 0xbfb8aa3b, v137
	v_exp_f32_e32 v134, v134
	v_pk_mul_f32 v[128:129], v[48:49], v[140:141]
	v_pk_mov_b32 v[140:141], v[142:143], v[90:91] op_sel:[1,0]
	v_pk_fma_f32 v[142:143], v[72:73], v[142:143], v[132:133]
	v_cvt_pk_bf16_f32 v48, v48, v49
	v_add_f32_e32 v49, 1.0, v127
	v_pk_fma_f32 v[142:143], v[74:75], v[140:141], v[142:143]
	v_rcp_f32_e32 v138, v49
	v_add_f32_e32 v49, 1.0, v134
	v_lshl_add_u64 v[144:145], s[14:15], 0, v[44:45]
	v_mul_f32_e32 v44, 0xbfb8aa3b, v142
	v_rcp_f32_e32 v139, v49
	v_exp_f32_e32 v45, v44
	v_mul_f32_e32 v49, 0xbfb8aa3b, v143
	v_exp_f32_e32 v49, v49
	v_lshl_add_u64 v[146:147], v[82:83], 1, v[144:145]
	v_cvt_pk_bf16_f32 v44, v128, v129
	v_pk_mul_f32 v[128:129], v[136:137], v[138:139]
	v_add_f32_e32 v45, 1.0, v45
	global_load_dwordx4 v[132:135], v[146:147], off
	v_pk_mul_f32 v[148:149], v[128:129], v[130:131]
	global_load_dwordx4 v[128:131], v[146:147], off offset:1024
	v_rcp_f32_e32 v146, v45
	v_add_f32_e32 v45, 1.0, v49
	v_rcp_f32_e32 v147, v45
	v_lshl_add_u64 v[144:145], v[84:85], 1, v[144:145]
	global_load_dwordx4 v[136:139], v[144:145], off
	v_pk_mul_f32 v[86:87], v[148:149], v[86:87]
	v_pk_fma_f32 v[92:93], v[70:71], v[140:141], v[92:93]
	v_cvt_pk_bf16_f32 v45, v86, v87
	v_pk_mul_f32 v[86:87], v[142:143], v[146:147]
	global_load_dwordx4 v[140:143], v[144:145], off offset:1024
	v_pk_fma_f32 v[88:89], v[68:69], v[90:91], v[76:77]
	v_pk_mov_b32 v[146:147], v[90:91], v[58:59] op_sel:[1,0]
	v_pk_fma_f32 v[90:91], v[72:73], v[90:91], v[92:93]
	v_pk_fma_f32 v[88:89], v[70:71], v[146:147], v[88:89]
	v_pk_fma_f32 v[90:91], v[74:75], v[146:147], v[90:91]
	v_mov_b32_e32 v62, v59
	v_mul_f32_e32 v92, 0xbfb8aa3b, v90
	v_mul_f32_e32 v93, 0xbfb8aa3b, v91
	v_exp_f32_e32 v92, v92
	v_exp_f32_e32 v93, v93
	v_pk_mul_f32 v[38:39], v[86:87], v[38:39]
	v_pk_fma_f32 v[88:89], v[72:73], v[58:59], v[88:89]
	v_add_f32_e32 v86, 1.0, v92
	v_add_f32_e32 v87, 1.0, v93
	v_rcp_f32_e32 v86, v86
	v_rcp_f32_e32 v87, v87
	v_pk_fma_f32 v[88:89], v[74:75], v[62:63], v[88:89]
	v_pk_mul_f32 v[56:57], v[38:39], v[56:57]
	v_cvt_pk_bf16_f32 v38, v38, v39
	v_mul_f32_e32 v39, 0xbfb8aa3b, v88
	v_cvt_pk_bf16_f32 v56, v56, v57
	v_exp_f32_e32 v39, v39
	v_mul_f32_e32 v57, 0xbfb8aa3b, v89
	v_exp_f32_e32 v57, v57
	v_pk_mul_f32 v[86:87], v[90:91], v[86:87]
	v_add_f32_e32 v39, 1.0, v39
	v_pk_mul_f32 v[40:41], v[86:87], v[40:41]
	v_rcp_f32_e32 v86, v39
	v_pk_mul_f32 v[54:55], v[40:41], v[54:55]
	v_add_f32_e32 v39, 1.0, v57
	v_cvt_pk_bf16_f32 v57, v54, v55
	v_pk_fma_f32 v[54:55], v[68:69], v[58:59], v[76:77]
	v_mov_b32_e32 v64, v63
	v_pk_fma_f32 v[54:55], v[70:71], v[62:63], v[54:55]
	v_mov_b32_e32 v60, v65
	v_pk_fma_f32 v[54:55], v[72:73], v[64:65], v[54:55]
	v_rcp_f32_e32 v87, v39
	v_pk_fma_f32 v[54:55], v[74:75], v[60:61], v[54:55]
	v_cvt_pk_bf16_f32 v39, v40, v41
	v_mul_f32_e32 v58, 0xbfb8aa3b, v54
	v_exp_f32_e32 v58, v58
	v_mul_f32_e32 v59, 0xbfb8aa3b, v55
	v_exp_f32_e32 v59, v59
	v_pk_mul_f32 v[40:41], v[88:89], v[86:87]
	v_cvt_pk_bf16_f32 v49, v148, v149
	v_pk_mul_f32 v[34:35], v[40:41], v[34:35]
	v_add_f32_e32 v40, 1.0, v58
	v_rcp_f32_e32 v60, v40
	v_add_f32_e32 v40, 1.0, v59
	v_rcp_f32_e32 v61, v40
	v_pk_mul_f32 v[50:51], v[34:35], v[50:51]
	v_cvt_pk_bf16_f32 v40, v34, v35
	v_cvt_pk_bf16_f32 v58, v50, v51
	v_pk_mul_f32 v[34:35], v[54:55], v[60:61]
	s_nop 0
	v_pk_mul_f32 v[34:35], v[34:35], v[36:37]
	s_nop 0
	v_pk_mul_f32 v[36:37], v[34:35], v[52:53]
	v_cvt_pk_bf16_f32 v41, v34, v35
	v_add_u32_e32 v34, v100, v107
	v_cvt_pk_bf16_f32 v59, v36, v37
	ds_write_b128 v114, v[46:49] offset:1024
	ds_write_b128 v114, v[38:41] offset:1040
	ds_write_b128 v114, v[42:45] offset:10240
	ds_write_b128 v114, v[56:59] offset:10256
	s_waitcnt vmcnt(3)
	ds_write_b128 v34, v[132:135]
	ds_write_b16 v115, v132
	ds_write_b16_d16_hi v115, v132 offset:144
	ds_write_b16 v115, v133 offset:288
	ds_write_b16_d16_hi v115, v133 offset:432
	ds_write_b16 v115, v134 offset:576
	ds_write_b16_d16_hi v115, v134 offset:720
	ds_write_b16 v115, v135 offset:864
	ds_write_b16_d16_hi v115, v135 offset:1008
	v_add_u32_e32 v34, v101, v107
	s_waitcnt vmcnt(2)
	ds_write_b128 v34, v[128:131]
	v_add_u32_e32 v34, v100, v108
	s_waitcnt vmcnt(1)
	ds_write_b128 v34, v[136:139]
	ds_write_b16 v116, v136
	ds_write_b16_d16_hi v116, v136 offset:144
	ds_write_b16 v116, v137 offset:288
	ds_write_b16_d16_hi v116, v137 offset:432
	ds_write_b16 v116, v138 offset:576
	ds_write_b16_d16_hi v116, v138 offset:720
	ds_write_b16 v116, v139 offset:864
	ds_write_b16_d16_hi v116, v139 offset:1008
	v_add_u32_e32 v34, v101, v108
	s_waitcnt vmcnt(0)
	ds_write_b128 v34, v[140:143]
	s_waitcnt lgkmcnt(0)
	s_barrier
	ds_read_b128 v[34:37], v122
	ds_read_b128 v[38:41], v122 offset:64
	ds_read_b128 v[42:45], v123
	ds_read_b128 v[46:49], v123 offset:64
	s_waitcnt lgkmcnt(1)
	v_mfma_f32_16x16x32_bf16 v[34:37], v[34:37], v[42:45], 0
	ds_read_b128 v[42:45], v122 offset:128
	s_waitcnt lgkmcnt(1)
	v_mfma_f32_16x16x32_bf16 v[34:37], v[38:41], v[46:49], v[34:37]
	ds_read_b128 v[38:41], v122 offset:192
	ds_read_b128 v[46:49], v123 offset:128
	ds_read_b128 v[50:53], v123 offset:192
	ds_read2st64_b32 v[86:87], v102 offset1:1
	s_waitcnt lgkmcnt(2)
	v_mfma_f32_16x16x32_bf16 v[34:37], v[42:45], v[46:49], v[34:37]
	s_waitcnt lgkmcnt(1)
	v_mfma_f32_16x16x32_bf16 v[34:37], v[38:41], v[50:53], v[34:37]
	s_and_saveexec_b64 s[0:1], s[20:21]
	s_cbranch_execz .LBB0_282
	ds_read_b32 v38, v109
	s_waitcnt lgkmcnt(0)
	v_sub_f32_e32 v38, v86, v38
	v_mul_f32_e32 v38, 0x3fb8aa3b, v38
	v_exp_f32_e32 v38, v38
	s_nop 0
	v_mul_f32_e32 v126, v34, v38
